# scanA GLA state MFMA re-tiled the same way (16-byte state stores)
# baseline (speedup 1.0000x reference)
.LBB0_1212:
	s_or_b64 exec, exec, s[0:1]
	v_and_b32_e32 v38, 0xffff, v30
	v_lshrrev_b32_e32 v30, 16, v30
	v_lshl_or_b32 v38, v34, 16, v38
	v_and_or_b32 v30, v34, s38, v30
	v_add_u32_e32 v34, 0x5000, v95
	ds_write2_b32 v34, v38, v30 offset1:36
	v_and_b32_e32 v30, 0xffff, v31
	v_lshrrev_b32_e32 v31, 16, v31
	v_lshl_or_b32 v30, v35, 16, v30
	v_and_or_b32 v31, v35, s38, v31
	ds_write2_b32 v34, v30, v31 offset0:72 offset1:108
	v_and_b32_e32 v30, 0xffff, v32
	v_lshrrev_b32_e32 v31, 16, v32
	v_lshl_or_b32 v30, v36, 16, v30
	v_and_or_b32 v31, v36, s38, v31
	ds_write2_b32 v34, v30, v31 offset0:144 offset1:180
	v_and_b32_e32 v30, 0xffff, v33
	v_lshrrev_b32_e32 v31, 16, v33
	v_lshl_or_b32 v30, v37, 16, v30
	v_and_or_b32 v31, v37, s38, v31
	ds_write2_b32 v34, v30, v31 offset0:216 offset1:252
	v_and_b32_e32 v30, 0xffff, v22
	v_lshrrev_b32_e32 v22, 16, v22
	v_lshl_or_b32 v30, v26, 16, v30
	v_and_or_b32 v22, v26, s38, v22
	v_add_u32_e32 v26, 0x5000, v96
	ds_write2_b32 v26, v30, v22 offset1:36
	v_and_b32_e32 v22, 0xffff, v23
	v_lshrrev_b32_e32 v23, 16, v23
	v_lshl_or_b32 v22, v27, 16, v22
	v_and_or_b32 v23, v27, s38, v23
	ds_write2_b32 v26, v22, v23 offset0:72 offset1:108
	v_and_b32_e32 v22, 0xffff, v24
	v_lshrrev_b32_e32 v23, 16, v24
	v_lshl_or_b32 v22, v28, 16, v22
	v_and_or_b32 v23, v28, s38, v23
	ds_write2_b32 v26, v22, v23 offset0:144 offset1:180
	v_and_b32_e32 v22, 0xffff, v25
	v_lshrrev_b32_e32 v23, 16, v25
	v_lshl_or_b32 v22, v29, 16, v22
	v_and_or_b32 v23, v29, s38, v23
	ds_write2_b32 v26, v22, v23 offset0:216 offset1:252
	s_waitcnt lgkmcnt(0)
	s_barrier
	s_add_i32 s27, s27, s28
	s_add_i32 s29, s29, s30
	v_readfirstlane_b32 s98, v0
	v_and_b32_e32 v249, 15, v0
	v_bfe_u32 v250, v0, 4, 2
	s_lshr_b32 s98, s98, 6
	s_lshr_b32 s99, s98, 1
	s_and_b32 s100, s98, 1
	v_lshrrev_b32_e32 v246, 2, v249
	v_and_b32_e32 v247, 3, v249
	v_lshl_add_u32 v246, v246, 3, v247
	s_lshl_b32 s101, s99, 5
	v_add_u32_e32 v246, s101, v246
	v_mul_u32_u24_e32 v246, 0x90, v246
	v_lshl_add_u32 v246, v250, 4, v246
	s_lshl_b32 s101, s100, 7
	v_add_u32_e32 v247, s101, v249
	v_mul_u32_u24_e32 v247, 0x90, v247
	v_lshl_add_u32 v247, v250, 4, v247
	ds_read_b128 v[114:117], v246 offset:2048
	ds_read_b128 v[118:121], v246 offset:2112
	ds_read_b128 v[122:125], v246 offset:2624
	ds_read_b128 v[126:129], v246 offset:2688
	v_lshlrev_b32_e32 v248, 8, v249
	v_lshl_add_u32 v248, v250, 4, v248
	s_lshl_b32 s101, s100, 15
	v_add_u32_e32 v248, s101, v248
	s_lshl_b32 s101, s99, 6
	v_add_u32_e32 v248, s101, v248
	s_lshl_b32 s101, s16, 18
	s_lshl_b32 s98, s14, 16
	s_add_i32 s101, s101, s98
	s_add_u32 s98, s23, s101
	s_addc_u32 s99, s24, 0
	ds_read_b128 v[130:133], v247 offset:20480
	ds_read_b128 v[134:137], v247 offset:20544
	ds_read_b128 v[138:141], v247 offset:22784
	ds_read_b128 v[142:145], v247 offset:22848
	ds_read_b128 v[146:149], v247 offset:25088
	ds_read_b128 v[150:153], v247 offset:25152
	ds_read_b128 v[154:157], v247 offset:27392
	ds_read_b128 v[158:161], v247 offset:27456
	s_waitcnt lgkmcnt(6)
	v_mfma_f32_16x16x32_bf16 v[162:165], v[114:117], v[130:133], 0
	v_mfma_f32_16x16x32_bf16 v[166:169], v[122:125], v[130:133], 0
	v_mfma_f32_16x16x32_bf16 v[162:165], v[118:121], v[134:137], v[162:165]
	v_mfma_f32_16x16x32_bf16 v[166:169], v[126:129], v[134:137], v[166:169]
	s_waitcnt lgkmcnt(4)
	v_mfma_f32_16x16x32_bf16 v[170:173], v[114:117], v[138:141], 0
	v_mfma_f32_16x16x32_bf16 v[174:177], v[122:125], v[138:141], 0
	v_mfma_f32_16x16x32_bf16 v[170:173], v[118:121], v[142:145], v[170:173]
	v_mfma_f32_16x16x32_bf16 v[174:177], v[126:129], v[142:145], v[174:177]
	s_waitcnt lgkmcnt(2)
	v_mfma_f32_16x16x32_bf16 v[178:181], v[114:117], v[146:149], 0
	v_mfma_f32_16x16x32_bf16 v[182:185], v[122:125], v[146:149], 0
	v_mfma_f32_16x16x32_bf16 v[178:181], v[118:121], v[150:153], v[178:181]
	v_mfma_f32_16x16x32_bf16 v[182:185], v[126:129], v[150:153], v[182:185]
	s_waitcnt lgkmcnt(0)
	v_mfma_f32_16x16x32_bf16 v[186:189], v[114:117], v[154:157], 0
	v_mfma_f32_16x16x32_bf16 v[190:193], v[122:125], v[154:157], 0
	v_mfma_f32_16x16x32_bf16 v[186:189], v[118:121], v[158:161], v[186:189]
	v_mfma_f32_16x16x32_bf16 v[190:193], v[126:129], v[158:161], v[190:193]
	ds_read_b128 v[130:133], v247 offset:29696
	ds_read_b128 v[134:137], v247 offset:29760
	ds_read_b128 v[138:141], v247 offset:32000
	ds_read_b128 v[142:145], v247 offset:32064
	ds_read_b128 v[146:149], v247 offset:34304
	ds_read_b128 v[150:153], v247 offset:34368
	ds_read_b128 v[154:157], v247 offset:36608
	ds_read_b128 v[158:161], v247 offset:36672
	s_waitcnt lgkmcnt(6)
	v_mfma_f32_16x16x32_bf16 v[194:197], v[114:117], v[130:133], 0
	v_mfma_f32_16x16x32_bf16 v[198:201], v[122:125], v[130:133], 0
	v_mfma_f32_16x16x32_bf16 v[194:197], v[118:121], v[134:137], v[194:197]
	v_mfma_f32_16x16x32_bf16 v[198:201], v[126:129], v[134:137], v[198:201]
	s_waitcnt lgkmcnt(4)
	v_mfma_f32_16x16x32_bf16 v[202:205], v[114:117], v[138:141], 0
	v_mfma_f32_16x16x32_bf16 v[206:209], v[122:125], v[138:141], 0
	v_mfma_f32_16x16x32_bf16 v[202:205], v[118:121], v[142:145], v[202:205]
	v_mfma_f32_16x16x32_bf16 v[206:209], v[126:129], v[142:145], v[206:209]
	s_waitcnt lgkmcnt(2)
	v_mfma_f32_16x16x32_bf16 v[230:233], v[114:117], v[146:149], 0
	v_mfma_f32_16x16x32_bf16 v[234:237], v[122:125], v[146:149], 0
	v_mfma_f32_16x16x32_bf16 v[230:233], v[118:121], v[150:153], v[230:233]
	v_mfma_f32_16x16x32_bf16 v[234:237], v[126:129], v[150:153], v[234:237]
	s_waitcnt lgkmcnt(0)
	v_mfma_f32_16x16x32_bf16 v[238:241], v[114:117], v[154:157], 0
	v_mfma_f32_16x16x32_bf16 v[242:245], v[122:125], v[154:157], 0
	v_mfma_f32_16x16x32_bf16 v[238:241], v[118:121], v[158:161], v[238:241]
	v_mfma_f32_16x16x32_bf16 v[242:245], v[126:129], v[158:161], v[242:245]
	s_nop 7
	s_nop 1
	v_cvt_pk_bf16_f32 v162, v162, v163
	v_cvt_pk_bf16_f32 v163, v164, v165
	v_cvt_pk_bf16_f32 v164, v166, v167
	v_cvt_pk_bf16_f32 v165, v168, v169
	global_store_dwordx4 v248, v[162:165], s[98:99]
	v_cvt_pk_bf16_f32 v170, v170, v171
	v_cvt_pk_bf16_f32 v171, v172, v173
	v_cvt_pk_bf16_f32 v172, v174, v175
	v_cvt_pk_bf16_f32 v173, v176, v177
	v_add_u32_e32 v248, 0x1000, v248
	global_store_dwordx4 v248, v[170:173], s[98:99]
	v_cvt_pk_bf16_f32 v178, v178, v179
	v_cvt_pk_bf16_f32 v179, v180, v181
	v_cvt_pk_bf16_f32 v180, v182, v183
	v_cvt_pk_bf16_f32 v181, v184, v185
	v_add_u32_e32 v248, 0x1000, v248
	global_store_dwordx4 v248, v[178:181], s[98:99]
	v_cvt_pk_bf16_f32 v186, v186, v187
	v_cvt_pk_bf16_f32 v187, v188, v189
	v_cvt_pk_bf16_f32 v188, v190, v191
	v_cvt_pk_bf16_f32 v189, v192, v193
	v_add_u32_e32 v248, 0x1000, v248
	global_store_dwordx4 v248, v[186:189], s[98:99]
	v_cvt_pk_bf16_f32 v194, v194, v195
	v_cvt_pk_bf16_f32 v195, v196, v197
	v_cvt_pk_bf16_f32 v196, v198, v199
	v_cvt_pk_bf16_f32 v197, v200, v201
	v_add_u32_e32 v248, 0x1000, v248
	global_store_dwordx4 v248, v[194:197], s[98:99]
	v_cvt_pk_bf16_f32 v202, v202, v203
	v_cvt_pk_bf16_f32 v203, v204, v205
	v_cvt_pk_bf16_f32 v204, v206, v207
	v_cvt_pk_bf16_f32 v205, v208, v209
	v_add_u32_e32 v248, 0x1000, v248
	global_store_dwordx4 v248, v[202:205], s[98:99]
	v_cvt_pk_bf16_f32 v230, v230, v231
	v_cvt_pk_bf16_f32 v231, v232, v233
	v_cvt_pk_bf16_f32 v232, v234, v235
	v_cvt_pk_bf16_f32 v233, v236, v237
	v_add_u32_e32 v248, 0x1000, v248
	global_store_dwordx4 v248, v[230:233], s[98:99]
	v_cvt_pk_bf16_f32 v238, v238, v239
	v_cvt_pk_bf16_f32 v239, v240, v241
	v_cvt_pk_bf16_f32 v240, v242, v243
	v_cvt_pk_bf16_f32 v241, v244, v245
	v_add_u32_e32 v248, 0x1000, v248
	global_store_dwordx4 v248, v[238:241], s[98:99]
	s_mov_b32 s0, s43
	s_waitcnt vmcnt(8)
	v_lshlrev_b32_e32 v53, 16, v214
	v_lshlrev_b32_e32 v103, 16, v216
	v_lshlrev_b32_e32 v105, 16, v217
	v_lshlrev_b32_e32 v104, 16, v218
	v_lshlrev_b32_e32 v102, 16, v219
	v_lshlrev_b32_e32 v55, 16, v220
	v_lshlrev_b32_e32 v51, 16, v221
	v_lshlrev_b32_e32 v101, 16, v215
	v_lshlrev_b32_e32 v107, 16, v222
	v_lshlrev_b32_e32 v109, 16, v223
	v_lshlrev_b32_e32 v111, 16, v224
	v_lshlrev_b32_e32 v113, 16, v225
	v_lshlrev_b32_e32 v112, 16, v226
	v_lshlrev_b32_e32 v110, 16, v227
	v_lshlrev_b32_e32 v108, 16, v228
	v_lshlrev_b32_e32 v106, 16, v229
	v_mov_b64_e32 v[32:33], v[4:5]
	v_mov_b64_e32 v[36:37], v[12:13]
	v_mov_b64_e32 v[24:25], v[16:17]
	v_mov_b64_e32 v[28:29], v[20:21]
	v_mov_b64_e32 v[40:41], v[8:9]
	s_andn2_b64 vcc, exec, s[12:13]
	v_mov_b64_e32 v[30:31], v[2:3]
	v_mov_b64_e32 v[34:35], v[10:11]
	v_mov_b64_e32 v[22:23], v[14:15]
	v_mov_b64_e32 v[26:27], v[18:19]
	v_mov_b64_e32 v[38:39], v[6:7]
	v_mov_b32_e32 v68, v51
	v_mov_b32_e32 v69, v53
	v_mov_b32_e32 v70, v55
	v_mov_b32_e32 v71, v101
	v_mov_b32_e32 v74, v102
	v_mov_b32_e32 v75, v103
	v_mov_b32_e32 v72, v104
	v_mov_b32_e32 v73, v105
	v_mov_b32_e32 v60, v106
	v_mov_b32_e32 v61, v107
	v_mov_b32_e32 v62, v108
	v_mov_b32_e32 v63, v109
	v_mov_b32_e32 v66, v110
	v_mov_b32_e32 v67, v111
	v_mov_b32_e32 v64, v112
	v_mov_b32_e32 v65, v113
	s_barrier
	s_cbranch_vccz .LBB0_1219
